# baseline (speedup 1.0000x reference)
; DEVI float gelu_exact(float x) { return 0.5f * x * (1.f + erff(x * 0.70710678118654752f)); }
; template <int EPI, int NRM>
; DEVI void epilogue(acc_t& acc, int pn, int trow, const EpiArgs& e, const float* rl, bf16* shmx) {
;   int tid_ = threadIdx.x; asm volatile("" : "+v"(tid_));
;   const int wid = tid_ >> 6, lane = tid_ & 63, wr = wid >> 2, wc = wid & 3, fr = lane & 15, fq = lane >> 4;
;   const int fl0 = wr * 64 + fq * 4;
;   const int tk0 = trow + wc * 32 + fr;
;   float rs[2][2];
;   if constexpr (NRM) {
; #pragma unroll
;     for (int bj = 0; bj < 2; ++bj)
; #pragma unroll
;       for (int n = 0; n < 2; ++n) rs[bj][n] = rl[wc * 32 + fr + bj * 128 + n * 16];
;     ...
;     if (dst != nullptr) {
; #pragma unroll
;       for (int ai = 0; ai < 2; ++ai)
; #pragma unroll
;         for (int bj = 0; bj < 2; ++bj)
; #pragma unroll
;           for (int m = 0; m < 4; ++m)
; #pragma unroll
;             for (int n = 0; n < 2; ++n) {
;               float r[4];
; #pragma unroll
;               for (int j = 0; j < 4; ++j) { r[j] = acc[ai][bj][m][n][j] * rs[bj][n]; if (act) r[j] = gelu_exact(r[j]); }
;               uint2 o; o.x = pack2(r[0], r[1]); o.y = pack2(r[2], r[3]);
;               const unsigned off = (unsigned)((tk0 + bj * 128 + n * 16) * ldo + fbase + ai * 128 + m * 16 + fl0);
;               *reinterpret_cast<uint2*>(dst + off) = o;
;             }
.LBB0_162:
	v_and_b32_e32 v170, 15, v136
	v_bfe_u32 v171, v136, 4, 2
	v_lshrrev_b32_e32 v172, 6, v136
	v_and_b32_e32 v173, 3, v172
	v_lshrrev_b32_e32 v174, 2, v172
	v_lshlrev_b32_e32 v175, 13, v173
	v_lshl_add_u32 v175, v174, 16, v175
	v_add_u32_e32 v175, 0x8000, v175
	v_lshl_add_u32 v176, v170, 7, v175
	v_and_b32_e32 v177, 1, v171
	v_lshl_add_u32 v176, v177, 3, v176
	v_lshrrev_b32_e32 v177, 1, v171
	v_and_b32_e32 v178, 7, v170
	v_add_u32_e32 v179, 0, v177
	v_xor_b32_e32 v179, v179, v178
	v_lshl_add_u32 v164, v179, 4, v176
	v_add_u32_e32 v179, 2, v177
	v_xor_b32_e32 v179, v179, v178
	v_lshl_add_u32 v165, v179, 4, v176
	v_add_u32_e32 v179, 4, v177
	v_xor_b32_e32 v179, v179, v178
	v_lshl_add_u32 v166, v179, 4, v176
	v_add_u32_e32 v179, 6, v177
	v_xor_b32_e32 v179, v179, v178
	v_lshl_add_u32 v167, v179, 4, v176
	v_and_b32_e32 v180, 63, v136
	v_lshl_add_u32 v168, v180, 4, v175
	v_lshrrev_b32_e32 v181, 3, v180
	v_and_b32_e32 v182, 7, v180
	v_xor_b32_e32 v182, v182, v181
	s_lshl_b32 s13, s10, 8
	v_lshl_add_u32 v183, v173, 5, v181
	v_add_u32_e32 v183, s13, v183
	v_lshlrev_b32_e32 v183, 11, v183
	s_lshl_b32 s13, s16, 8
	v_lshl_add_u32 v179, v174, 6, s13
	v_lshl_add_u32 v179, v182, 3, v179
	v_add_lshl_u32 v169, v183, v179, 1
	s_lshl_b32 s13, s19, 10
	v_mov_b32_e32 v130, v136
	s_and_b32 s13, s13, 0x400
	s_add_i32 s13, s13, 0
	v_lshrrev_b32_e32 v132, 1, v130
	v_and_b32_e32 v141, 15, v130
	v_and_b32_e32 v143, 0x60, v132
	s_add_i32 s13, s13, 0x20000
	v_lshlrev_b32_e32 v132, 2, v143
	v_lshlrev_b32_e32 v133, 2, v141
	v_add3_u32 v132, s13, v132, v133
	ds_read2_b32 v[134:135], v132 offset1:16
	ds_read2_b32 v[132:133], v132 offset0:128 offset1:144
	s_lshl_b32 s10, s10, 8
	v_lshrrev_b32_e32 v142, 2, v130
	v_or3_b32 v141, v141, s10, v143
	v_ashrrev_i32_e32 v130, 2, v130
	s_lshl_b32 s10, s16, 8
	v_and_b32_e32 v130, 0xffffffc0, v130
	v_lshlrev_b32_e32 v141, 11, v141
	v_and_or_b32 v142, v142, 12, s10
	v_add3_u32 v130, v142, v130, v141
	s_waitcnt lgkmcnt(1)
	v_mul_f32_e32 v141, v126, v134
	v_mul_f32_e32 v142, v127, v134
	v_mul_f32_e32 v128, v128, v134
	v_mul_f32_e32 v129, v129, v134
	v_lshl_add_u64 v[126:127], v[130:131], 1, s[2:3]
	v_cvt_pk_bf16_f32 v129, v128, v129
	v_cvt_pk_bf16_f32 v128, v141, v142
	ds_write_b64 v164, v[128:129]
	v_mul_f32_e32 v126, v122, v135
	v_mul_f32_e32 v127, v123, v135
	v_mul_f32_e32 v124, v124, v135
	v_mul_f32_e32 v125, v125, v135
	v_add_u32_e32 v122, 0x8000, v130
	v_mov_b32_e32 v123, v131
	v_lshl_add_u64 v[122:123], v[122:123], 1, s[2:3]
	v_cvt_pk_bf16_f32 v125, v124, v125
	v_cvt_pk_bf16_f32 v124, v126, v127
	ds_write_b64 v164, v[124:125] offset:2048
	v_or_b32_e32 v122, 16, v130
	v_mul_f32_e32 v124, v118, v134
	v_mul_f32_e32 v125, v119, v134
	v_mul_f32_e32 v120, v120, v134
	v_mul_f32_e32 v121, v121, v134
	v_mov_b32_e32 v123, v131
	v_lshl_add_u64 v[118:119], v[122:123], 1, s[2:3]
	v_cvt_pk_bf16_f32 v121, v120, v121
	v_cvt_pk_bf16_f32 v120, v124, v125
	ds_write_b64 v165, v[120:121]
	v_mul_f32_e32 v118, v114, v135
	v_mul_f32_e32 v119, v115, v135
	v_mul_f32_e32 v116, v116, v135
	v_mul_f32_e32 v117, v117, v135
	v_add_u32_e32 v114, 0x8010, v130
	v_mov_b32_e32 v115, v131
	v_lshl_add_u64 v[114:115], v[114:115], 1, s[2:3]
	v_cvt_pk_bf16_f32 v117, v116, v117
	v_cvt_pk_bf16_f32 v116, v118, v119
	ds_write_b64 v165, v[116:117] offset:2048
	v_or_b32_e32 v114, 32, v130
	v_mul_f32_e32 v116, v110, v134
	v_mul_f32_e32 v117, v111, v134
	v_mul_f32_e32 v112, v112, v134
	v_mul_f32_e32 v113, v113, v134
	v_mov_b32_e32 v115, v131
	v_lshl_add_u64 v[110:111], v[114:115], 1, s[2:3]
	v_cvt_pk_bf16_f32 v113, v112, v113
	v_cvt_pk_bf16_f32 v112, v116, v117
	ds_write_b64 v166, v[112:113]
	v_mul_f32_e32 v110, v106, v135
	v_mul_f32_e32 v111, v107, v135
	v_mul_f32_e32 v108, v108, v135
	v_mul_f32_e32 v109, v109, v135
	v_add_u32_e32 v106, 0x8020, v130
	v_mov_b32_e32 v107, v131
	v_lshl_add_u64 v[106:107], v[106:107], 1, s[2:3]
	v_cvt_pk_bf16_f32 v109, v108, v109
	v_cvt_pk_bf16_f32 v108, v110, v111
	ds_write_b64 v166, v[108:109] offset:2048
	v_or_b32_e32 v106, 48, v130
	v_mul_f32_e32 v108, v102, v134
	v_mul_f32_e32 v109, v103, v134
	v_mul_f32_e32 v104, v104, v134
	v_mul_f32_e32 v105, v105, v134
	v_mov_b32_e32 v107, v131
	v_lshl_add_u64 v[102:103], v[106:107], 1, s[2:3]
	v_cvt_pk_bf16_f32 v105, v104, v105
	v_cvt_pk_bf16_f32 v104, v108, v109
	ds_write_b64 v167, v[104:105]
	v_mul_f32_e32 v102, v98, v135
	v_mul_f32_e32 v103, v99, v135
	v_mul_f32_e32 v100, v100, v135
	v_mul_f32_e32 v101, v101, v135
	v_add_u32_e32 v98, 0x8030, v130
	v_mov_b32_e32 v99, v131
	v_lshl_add_u64 v[98:99], v[98:99], 1, s[2:3]
	v_cvt_pk_bf16_f32 v101, v100, v101
	v_cvt_pk_bf16_f32 v100, v102, v103
	ds_write_b64 v167, v[100:101] offset:2048
	v_add_u32_e32 v98, 0x40000, v130
	s_waitcnt lgkmcnt(0)
; DEVI float gelu_exact(float x) { return 0.5f * x * (1.f + erff(x * 0.70710678118654752f)); }
; template <int EPI, int NRM>
; DEVI void epilogue(acc_t& acc, int pn, int trow, const EpiArgs& e, const float* rl, bf16* shmx) {
;     ...
;     if (dst != nullptr) {
; #pragma unroll
;       for (int ai = 0; ai < 2; ++ai)
; #pragma unroll
;         for (int bj = 0; bj < 2; ++bj)
; #pragma unroll
;           for (int m = 0; m < 4; ++m)
; #pragma unroll
;             for (int n = 0; n < 2; ++n) {
;               float r[4];
; #pragma unroll
;               for (int j = 0; j < 4; ++j) { r[j] = acc[ai][bj][m][n][j] * rs[bj][n]; if (act) r[j] = gelu_exact(r[j]); }
;               uint2 o; o.x = pack2(r[0], r[1]); o.y = pack2(r[2], r[3]);
;               const unsigned off = (unsigned)((tk0 + bj * 128 + n * 16) * ldo + fbase + ai * 128 + m * 16 + fl0);
;               *reinterpret_cast<uint2*>(dst + off) = o;
;             }
	v_mul_f32_e32 v100, v94, v132
	v_mul_f32_e32 v101, v95, v132
	v_mul_f32_e32 v96, v96, v132
	v_mul_f32_e32 v97, v97, v132
	v_mov_b32_e32 v99, v131
	v_lshl_add_u64 v[94:95], v[98:99], 1, s[2:3]
	v_cvt_pk_bf16_f32 v97, v96, v97
	v_cvt_pk_bf16_f32 v96, v100, v101
	ds_write_b64 v164, v[96:97] offset:4096
	v_mul_f32_e32 v94, v90, v133
	v_mul_f32_e32 v95, v91, v133
	v_mul_f32_e32 v92, v92, v133
	v_mul_f32_e32 v93, v93, v133
	v_add_u32_e32 v90, 0x48000, v130
	v_mov_b32_e32 v91, v131
	v_lshl_add_u64 v[90:91], v[90:91], 1, s[2:3]
	v_cvt_pk_bf16_f32 v93, v92, v93
	v_cvt_pk_bf16_f32 v92, v94, v95
	ds_write_b64 v164, v[92:93] offset:6144
	v_add_u32_e32 v90, 0x40010, v130
	v_mul_f32_e32 v92, v86, v132
	v_mul_f32_e32 v93, v87, v132
	v_mul_f32_e32 v88, v88, v132
	v_mul_f32_e32 v89, v89, v132
	v_mov_b32_e32 v91, v131
	v_lshl_add_u64 v[86:87], v[90:91], 1, s[2:3]
	v_cvt_pk_bf16_f32 v89, v88, v89
	v_cvt_pk_bf16_f32 v88, v92, v93
	ds_write_b64 v165, v[88:89] offset:4096
	v_mul_f32_e32 v86, v82, v133
	v_mul_f32_e32 v87, v83, v133
	v_mul_f32_e32 v84, v84, v133
	v_mul_f32_e32 v85, v85, v133
	v_add_u32_e32 v82, 0x48010, v130
	v_mov_b32_e32 v83, v131
	v_lshl_add_u64 v[82:83], v[82:83], 1, s[2:3]
	v_cvt_pk_bf16_f32 v85, v84, v85
	v_cvt_pk_bf16_f32 v84, v86, v87
	ds_write_b64 v165, v[84:85] offset:6144
	v_add_u32_e32 v82, 0x40020, v130
	v_mul_f32_e32 v84, v78, v132
	v_mul_f32_e32 v85, v79, v132
	v_mul_f32_e32 v80, v80, v132
	v_mul_f32_e32 v81, v81, v132
	v_mov_b32_e32 v83, v131
	v_lshl_add_u64 v[78:79], v[82:83], 1, s[2:3]
	v_cvt_pk_bf16_f32 v81, v80, v81
	v_cvt_pk_bf16_f32 v80, v84, v85
	ds_write_b64 v166, v[80:81] offset:4096
	v_mul_f32_e32 v78, v74, v133
	v_mul_f32_e32 v79, v75, v133
	v_mul_f32_e32 v76, v76, v133
	v_mul_f32_e32 v77, v77, v133
	v_add_u32_e32 v74, 0x48020, v130
	v_mov_b32_e32 v75, v131
	v_lshl_add_u64 v[74:75], v[74:75], 1, s[2:3]
	v_cvt_pk_bf16_f32 v77, v76, v77
	v_cvt_pk_bf16_f32 v76, v78, v79
	ds_write_b64 v166, v[76:77] offset:6144
	v_add_u32_e32 v74, 0x40030, v130
	v_mul_f32_e32 v76, v70, v132
	v_mul_f32_e32 v77, v71, v132
	v_mul_f32_e32 v72, v72, v132
	v_mul_f32_e32 v73, v73, v132
	v_mov_b32_e32 v75, v131
	v_lshl_add_u64 v[70:71], v[74:75], 1, s[2:3]
	v_cvt_pk_bf16_f32 v73, v72, v73
	v_cvt_pk_bf16_f32 v72, v76, v77
	ds_write_b64 v167, v[72:73] offset:4096
	v_mul_f32_e32 v70, v62, v133
	v_mul_f32_e32 v71, v63, v133
	v_mul_f32_e32 v64, v64, v133
	v_mul_f32_e32 v65, v65, v133
	v_add_u32_e32 v62, 0x48030, v130
	v_mov_b32_e32 v63, v131
	v_lshl_add_u64 v[62:63], v[62:63], 1, s[2:3]
	v_cvt_pk_bf16_f32 v65, v64, v65
	v_cvt_pk_bf16_f32 v64, v70, v71
	ds_write_b64 v167, v[64:65] offset:6144
	s_waitcnt lgkmcnt(0)
	ds_read_b128 v[172:175], v168
	ds_read_b128 v[176:179], v168 offset:1024
	ds_read_b128 v[180:183], v168 offset:2048
	ds_read_b128 v[184:187], v168 offset:3072
	ds_read_b128 v[188:191], v168 offset:4096
	ds_read_b128 v[192:195], v168 offset:5120
	ds_read_b128 v[196:199], v168 offset:6144
	ds_read_b128 v[200:203], v168 offset:7168
	v_add_u32_e32 v204, 0x0, v169
	v_add_u32_e32 v205, 0x8000, v169
	v_add_u32_e32 v206, 0x10000, v169
	v_add_u32_e32 v207, 0x18000, v169
	v_add_u32_e32 v208, 0x80000, v169
	v_add_u32_e32 v209, 0x88000, v169
	v_add_u32_e32 v210, 0x90000, v169
	v_add_u32_e32 v211, 0x98000, v169
	s_waitcnt lgkmcnt(7)
	global_store_dwordx4 v204, v[172:175], s[2:3]
	s_waitcnt lgkmcnt(6)
	global_store_dwordx4 v205, v[176:179], s[2:3]
	s_waitcnt lgkmcnt(5)
	global_store_dwordx4 v206, v[180:183], s[2:3]
	s_waitcnt lgkmcnt(4)
	global_store_dwordx4 v207, v[184:187], s[2:3]
	s_waitcnt lgkmcnt(3)
	global_store_dwordx4 v208, v[188:191], s[2:3]
	s_waitcnt lgkmcnt(2)
	global_store_dwordx4 v209, v[192:195], s[2:3]
	s_waitcnt lgkmcnt(1)
	global_store_dwordx4 v210, v[196:199], s[2:3]
	s_waitcnt lgkmcnt(0)
; DEVI float gelu_exact(float x) { return 0.5f * x * (1.f + erff(x * 0.70710678118654752f)); }
; template <int EPI, int NRM>
; DEVI void epilogue(acc_t& acc, int pn, int trow, const EpiArgs& e, const float* rl, bf16* shmx) {
;     ...
;     if (dst != nullptr) {
; #pragma unroll
;       for (int ai = 0; ai < 2; ++ai)
; #pragma unroll
;         for (int bj = 0; bj < 2; ++bj)
; #pragma unroll
;           for (int m = 0; m < 4; ++m)
; #pragma unroll
;             for (int n = 0; n < 2; ++n) {
;               float r[4];
; #pragma unroll
;               for (int j = 0; j < 4; ++j) { r[j] = acc[ai][bj][m][n][j] * rs[bj][n]; if (act) r[j] = gelu_exact(r[j]); }
;               uint2 o; o.x = pack2(r[0], r[1]); o.y = pack2(r[2], r[3]);
;               const unsigned off = (unsigned)((tk0 + bj * 128 + n * 16) * ldo + fbase + ai * 128 + m * 16 + fl0);
;               *reinterpret_cast<uint2*>(dst + off) = o;
;             }
	global_store_dwordx4 v211, v[200:203], s[2:3]
	v_add_u32_e32 v62, 0x80, v130
	v_mul_f32_e32 v64, v66, v134
	v_mul_f32_e32 v66, v67, v134
	v_mul_f32_e32 v65, v68, v134
	v_mul_f32_e32 v67, v69, v134
	v_mov_b32_e32 v63, v131
	v_lshl_add_u64 v[62:63], v[62:63], 1, s[2:3]
	v_cvt_pk_bf16_f32 v65, v65, v67
	v_cvt_pk_bf16_f32 v64, v64, v66
	ds_write_b64 v164, v[64:65]
	v_mul_f32_e32 v62, v58, v135
	v_mul_f32_e32 v63, v59, v135
	v_mul_f32_e32 v60, v60, v135
	v_mul_f32_e32 v61, v61, v135
	v_add_u32_e32 v58, 0x8080, v130
	v_mov_b32_e32 v59, v131
	v_lshl_add_u64 v[58:59], v[58:59], 1, s[2:3]
	v_cvt_pk_bf16_f32 v61, v60, v61
	v_cvt_pk_bf16_f32 v60, v62, v63
	ds_write_b64 v164, v[60:61] offset:2048
	v_add_u32_e32 v58, 0x90, v130
	v_mul_f32_e32 v60, v54, v134
	v_mul_f32_e32 v61, v55, v134
	v_mul_f32_e32 v56, v56, v134
	v_mul_f32_e32 v57, v57, v134
	v_mov_b32_e32 v59, v131
	v_lshl_add_u64 v[54:55], v[58:59], 1, s[2:3]
	v_cvt_pk_bf16_f32 v57, v56, v57
	v_cvt_pk_bf16_f32 v56, v60, v61
	ds_write_b64 v165, v[56:57]
	v_mul_f32_e32 v54, v50, v135
	v_mul_f32_e32 v55, v51, v135
	v_mul_f32_e32 v52, v52, v135
	v_mul_f32_e32 v53, v53, v135
	v_add_u32_e32 v50, 0x8090, v130
	v_mov_b32_e32 v51, v131
	v_lshl_add_u64 v[50:51], v[50:51], 1, s[2:3]
	v_cvt_pk_bf16_f32 v53, v52, v53
	v_cvt_pk_bf16_f32 v52, v54, v55
	ds_write_b64 v165, v[52:53] offset:2048
	v_add_u32_e32 v50, 0xa0, v130
	v_mul_f32_e32 v52, v46, v134
	v_mul_f32_e32 v53, v47, v134
	v_mul_f32_e32 v48, v48, v134
	v_mul_f32_e32 v49, v49, v134
	v_mov_b32_e32 v51, v131
	v_lshl_add_u64 v[46:47], v[50:51], 1, s[2:3]
	v_cvt_pk_bf16_f32 v49, v48, v49
	v_cvt_pk_bf16_f32 v48, v52, v53
	ds_write_b64 v166, v[48:49]
	v_mul_f32_e32 v46, v42, v135
	v_mul_f32_e32 v47, v43, v135
	v_mul_f32_e32 v44, v44, v135
	v_mul_f32_e32 v45, v45, v135
	v_add_u32_e32 v42, 0x80a0, v130
	v_mov_b32_e32 v43, v131
	v_lshl_add_u64 v[42:43], v[42:43], 1, s[2:3]
	v_cvt_pk_bf16_f32 v45, v44, v45
	v_cvt_pk_bf16_f32 v44, v46, v47
	ds_write_b64 v166, v[44:45] offset:2048
	v_add_u32_e32 v42, 0xb0, v130
	v_mul_f32_e32 v44, v38, v134
	v_mul_f32_e32 v45, v39, v134
	v_mul_f32_e32 v40, v40, v134
	v_mul_f32_e32 v41, v41, v134
	v_mov_b32_e32 v43, v131
	v_lshl_add_u64 v[38:39], v[42:43], 1, s[2:3]
	v_cvt_pk_bf16_f32 v41, v40, v41
	v_cvt_pk_bf16_f32 v40, v44, v45
	ds_write_b64 v167, v[40:41]
	v_mul_f32_e32 v38, v34, v135
	v_mul_f32_e32 v39, v35, v135
	v_mul_f32_e32 v36, v36, v135
	v_mul_f32_e32 v37, v37, v135
	v_add_u32_e32 v34, 0x80b0, v130
	v_mov_b32_e32 v35, v131
	v_lshl_add_u64 v[34:35], v[34:35], 1, s[2:3]
	v_cvt_pk_bf16_f32 v37, v36, v37
	v_cvt_pk_bf16_f32 v36, v38, v39
	ds_write_b64 v167, v[36:37] offset:2048
	v_add_u32_e32 v34, 0x40080, v130
	v_mul_f32_e32 v36, v30, v132
	v_mul_f32_e32 v37, v31, v132
	v_mul_f32_e32 v32, v32, v132
	v_mul_f32_e32 v33, v33, v132
	v_mov_b32_e32 v35, v131
	v_lshl_add_u64 v[30:31], v[34:35], 1, s[2:3]
	v_cvt_pk_bf16_f32 v33, v32, v33
	v_cvt_pk_bf16_f32 v32, v36, v37
	ds_write_b64 v164, v[32:33] offset:4096
	v_mul_f32_e32 v30, v26, v133
	v_mul_f32_e32 v31, v27, v133
	v_mul_f32_e32 v28, v28, v133
	v_mul_f32_e32 v29, v29, v133
	v_add_u32_e32 v26, 0x48080, v130
	v_mov_b32_e32 v27, v131
	v_lshl_add_u64 v[26:27], v[26:27], 1, s[2:3]
	v_cvt_pk_bf16_f32 v29, v28, v29
	v_cvt_pk_bf16_f32 v28, v30, v31
	ds_write_b64 v164, v[28:29] offset:6144
	v_add_u32_e32 v26, 0x40090, v130
	v_mul_f32_e32 v28, v22, v132
	v_mul_f32_e32 v29, v23, v132
	v_mul_f32_e32 v24, v24, v132
	v_mul_f32_e32 v25, v25, v132
	v_mov_b32_e32 v27, v131
	v_lshl_add_u64 v[22:23], v[26:27], 1, s[2:3]
	v_cvt_pk_bf16_f32 v25, v24, v25
	v_cvt_pk_bf16_f32 v24, v28, v29
	ds_write_b64 v165, v[24:25] offset:4096
	v_mul_f32_e32 v22, v18, v133
	v_mul_f32_e32 v23, v19, v133
	v_mul_f32_e32 v20, v20, v133
	v_mul_f32_e32 v21, v21, v133
	v_add_u32_e32 v18, 0x48090, v130
	v_mov_b32_e32 v19, v131
	v_lshl_add_u64 v[18:19], v[18:19], 1, s[2:3]
	v_cvt_pk_bf16_f32 v21, v20, v21
	v_cvt_pk_bf16_f32 v20, v22, v23
	ds_write_b64 v165, v[20:21] offset:6144
	v_add_u32_e32 v18, 0x400a0, v130
	v_mul_f32_e32 v20, v14, v132
	v_mul_f32_e32 v21, v15, v132
	v_mul_f32_e32 v16, v16, v132
	v_mul_f32_e32 v17, v17, v132
	v_mov_b32_e32 v19, v131
	v_lshl_add_u64 v[14:15], v[18:19], 1, s[2:3]
	v_cvt_pk_bf16_f32 v17, v16, v17
	v_cvt_pk_bf16_f32 v16, v20, v21
	ds_write_b64 v166, v[16:17] offset:4096
	v_mul_f32_e32 v14, v10, v133
	v_mul_f32_e32 v15, v11, v133
	v_mul_f32_e32 v12, v12, v133
	v_mul_f32_e32 v13, v13, v133
	v_add_u32_e32 v10, 0x480a0, v130
	v_mov_b32_e32 v11, v131
	v_lshl_add_u64 v[10:11], v[10:11], 1, s[2:3]
	v_cvt_pk_bf16_f32 v13, v12, v13
	v_cvt_pk_bf16_f32 v12, v14, v15
	ds_write_b64 v166, v[12:13] offset:6144
	v_add_u32_e32 v10, 0x400b0, v130
	v_mul_f32_e32 v12, v6, v132
	v_mul_f32_e32 v13, v7, v132
	v_mul_f32_e32 v8, v8, v132
	v_mul_f32_e32 v9, v9, v132
	v_mov_b32_e32 v11, v131
	v_lshl_add_u64 v[6:7], v[10:11], 1, s[2:3]
	v_cvt_pk_bf16_f32 v9, v8, v9
	v_cvt_pk_bf16_f32 v8, v12, v13
	ds_write_b64 v167, v[8:9] offset:4096
	v_mul_f32_e32 v6, v2, v133
	v_mul_f32_e32 v7, v3, v133
	v_mul_f32_e32 v4, v4, v133
	v_mul_f32_e32 v5, v5, v133
	v_add_u32_e32 v130, 0x480b0, v130
	v_lshl_add_u64 v[2:3], v[130:131], 1, s[2:3]
	v_cvt_pk_bf16_f32 v5, v4, v5
	v_cvt_pk_bf16_f32 v4, v6, v7
	s_add_i32 s19, s19, 1
	s_andn2_b64 vcc, exec, s[4:5]
	s_mov_b32 s16, s12
	s_mov_b32 s10, s11
	ds_write_b64 v167, v[4:5] offset:6144
	s_waitcnt lgkmcnt(0)
	ds_read_b128 v[172:175], v168
	ds_read_b128 v[176:179], v168 offset:1024
	ds_read_b128 v[180:183], v168 offset:2048
	ds_read_b128 v[184:187], v168 offset:3072
	ds_read_b128 v[188:191], v168 offset:4096
	ds_read_b128 v[192:195], v168 offset:5120
	ds_read_b128 v[196:199], v168 offset:6144
	ds_read_b128 v[200:203], v168 offset:7168
	v_add_u32_e32 v204, 0x100, v169
	v_add_u32_e32 v205, 0x8100, v169
	v_add_u32_e32 v206, 0x10100, v169
	v_add_u32_e32 v207, 0x18100, v169
	v_add_u32_e32 v208, 0x80100, v169
	v_add_u32_e32 v209, 0x88100, v169
	v_add_u32_e32 v210, 0x90100, v169
	v_add_u32_e32 v211, 0x98100, v169
	s_waitcnt lgkmcnt(7)
	global_store_dwordx4 v204, v[172:175], s[2:3]
	s_waitcnt lgkmcnt(6)
	global_store_dwordx4 v205, v[176:179], s[2:3]
	s_waitcnt lgkmcnt(5)
	global_store_dwordx4 v206, v[180:183], s[2:3]
	s_waitcnt lgkmcnt(4)
	global_store_dwordx4 v207, v[184:187], s[2:3]
	s_waitcnt lgkmcnt(3)
	global_store_dwordx4 v208, v[188:191], s[2:3]
	s_waitcnt lgkmcnt(2)
	global_store_dwordx4 v209, v[192:195], s[2:3]
	s_waitcnt lgkmcnt(1)
	global_store_dwordx4 v210, v[196:199], s[2:3]
	s_waitcnt lgkmcnt(0)
	global_store_dwordx4 v211, v[200:203], s[2:3]
	s_cbranch_vccz .LBB0_179

; DEVI float gelu_exact(float x) { return 0.5f * x * (1.f + erff(x * 0.70710678118654752f)); }
; template <int EPI, int NRM>
; DEVI void epilogue(acc_t& acc, int pn, int trow, const EpiArgs& e, const float* rl, bf16* shmx) {
;   int tid_ = threadIdx.x; asm volatile("" : "+v"(tid_));
;   const int wid = tid_ >> 6, lane = tid_ & 63, wr = wid >> 2, wc = wid & 3, fr = lane & 15, fq = lane >> 4;
;   const int fl0 = wr * 64 + fq * 4;
;   const int tk0 = trow + wc * 32 + fr;
;   float rs[2][2];
;   if constexpr (NRM) {
; #pragma unroll
;     for (int bj = 0; bj < 2; ++bj)
; #pragma unroll
;       for (int n = 0; n < 2; ++n) rs[bj][n] = rl[wc * 32 + fr + bj * 128 + n * 16];
;     ...
;     if (dst != nullptr) {
; #pragma unroll
;       for (int ai = 0; ai < 2; ++ai)
; #pragma unroll
;         for (int bj = 0; bj < 2; ++bj)
; #pragma unroll
;           for (int m = 0; m < 4; ++m)
; #pragma unroll
;             for (int n = 0; n < 2; ++n) {
;               float r[4];
; #pragma unroll
;               for (int j = 0; j < 4; ++j) { r[j] = acc[ai][bj][m][n][j] * rs[bj][n]; if (act) r[j] = gelu_exact(r[j]); }
;               uint2 o; o.x = pack2(r[0], r[1]); o.y = pack2(r[2], r[3]);
;               const unsigned off = (unsigned)((tk0 + bj * 128 + n * 16) * ldo + fbase + ai * 128 + m * 16 + fl0);
;               *reinterpret_cast<uint2*>(dst + off) = o;
;             }
.LBB0_1895:
	v_and_b32_e32 v170, 15, v1
	v_bfe_u32 v171, v1, 4, 2
	v_lshrrev_b32_e32 v172, 6, v1
	v_and_b32_e32 v173, 3, v172
	v_lshrrev_b32_e32 v174, 2, v172
	v_lshlrev_b32_e32 v175, 13, v173
	v_lshl_add_u32 v175, v174, 16, v175
	v_add_u32_e32 v175, 0x8000, v175
	v_lshl_add_u32 v176, v170, 7, v175
	v_and_b32_e32 v177, 1, v171
	v_lshl_add_u32 v176, v177, 3, v176
	v_lshrrev_b32_e32 v177, 1, v171
	v_and_b32_e32 v178, 7, v170
	v_add_u32_e32 v179, 0, v177
	v_xor_b32_e32 v179, v179, v178
	v_lshl_add_u32 v164, v179, 4, v176
	v_add_u32_e32 v179, 2, v177
	v_xor_b32_e32 v179, v179, v178
	v_lshl_add_u32 v165, v179, 4, v176
	v_add_u32_e32 v179, 4, v177
	v_xor_b32_e32 v179, v179, v178
	v_lshl_add_u32 v166, v179, 4, v176
	v_add_u32_e32 v179, 6, v177
	v_xor_b32_e32 v179, v179, v178
	v_lshl_add_u32 v167, v179, 4, v176
	v_and_b32_e32 v180, 63, v1
	v_lshl_add_u32 v168, v180, 4, v175
	v_lshrrev_b32_e32 v181, 3, v180
	v_and_b32_e32 v182, 7, v180
	v_xor_b32_e32 v182, v182, v181
	s_lshl_b32 s9, s12, 8
	v_lshl_add_u32 v183, v173, 5, v181
	v_add_u32_e32 v183, s9, v183
	v_lshlrev_b32_e32 v183, 11, v183
	s_lshl_b32 s9, s14, 8
	v_lshl_add_u32 v179, v174, 6, s9
	v_lshl_add_u32 v179, v182, 3, v179
	v_add_lshl_u32 v169, v183, v179, 1
	s_lshl_b32 s11, s17, 10
	v_mov_b32_e32 v132, v1
	s_and_b32 s11, s11, 0x400
	s_add_i32 s11, s11, 0
	v_lshrrev_b32_e32 v134, 1, v132
	v_and_b32_e32 v141, 15, v132
	v_and_b32_e32 v143, 0x60, v134
	s_add_i32 s11, s11, 0x20000
	v_lshlrev_b32_e32 v134, 2, v143
	v_lshlrev_b32_e32 v135, 2, v141
	v_add3_u32 v134, s11, v134, v135
	ds_read2_b32 v[136:137], v134 offset1:16
	ds_read2_b32 v[134:135], v134 offset0:128 offset1:144
	s_lshl_b32 s9, s12, 8
	v_lshrrev_b32_e32 v142, 2, v132
	v_or3_b32 v141, v141, s9, v143
	v_ashrrev_i32_e32 v132, 2, v132
	s_lshl_b32 s9, s14, 8
	v_and_b32_e32 v132, 0xffffffc0, v132
	v_lshlrev_b32_e32 v141, 11, v141
	v_and_or_b32 v142, v142, 12, s9
	v_add3_u32 v132, v142, v132, v141
	s_waitcnt lgkmcnt(1)
	v_mul_f32_e32 v141, v126, v136
	v_mul_f32_e32 v142, v127, v136
	v_mul_f32_e32 v128, v128, v136
	v_mul_f32_e32 v129, v129, v136
	v_lshl_add_u64 v[126:127], v[132:133], 1, s[2:3]
	v_cvt_pk_bf16_f32 v129, v128, v129
	v_cvt_pk_bf16_f32 v128, v141, v142
	ds_write_b64 v164, v[128:129]
	v_mul_f32_e32 v126, v122, v137
	v_mul_f32_e32 v127, v123, v137
	v_mul_f32_e32 v124, v124, v137
	v_mul_f32_e32 v125, v125, v137
	v_add_u32_e32 v122, 0x8000, v132
	v_mov_b32_e32 v123, v133
	v_lshl_add_u64 v[122:123], v[122:123], 1, s[2:3]
	v_cvt_pk_bf16_f32 v125, v124, v125
	v_cvt_pk_bf16_f32 v124, v126, v127
	ds_write_b64 v164, v[124:125] offset:2048
	v_or_b32_e32 v122, 16, v132
	v_mul_f32_e32 v124, v118, v136
	v_mul_f32_e32 v125, v119, v136
	v_mul_f32_e32 v120, v120, v136
	v_mul_f32_e32 v121, v121, v136
	v_mov_b32_e32 v123, v133
	v_lshl_add_u64 v[118:119], v[122:123], 1, s[2:3]
	v_cvt_pk_bf16_f32 v121, v120, v121
	v_cvt_pk_bf16_f32 v120, v124, v125
	ds_write_b64 v165, v[120:121]
	v_mul_f32_e32 v118, v114, v137
	v_mul_f32_e32 v119, v115, v137
	v_mul_f32_e32 v116, v116, v137
	v_mul_f32_e32 v117, v117, v137
	v_add_u32_e32 v114, 0x8010, v132
	v_mov_b32_e32 v115, v133
	v_lshl_add_u64 v[114:115], v[114:115], 1, s[2:3]
	v_cvt_pk_bf16_f32 v117, v116, v117
	v_cvt_pk_bf16_f32 v116, v118, v119
	ds_write_b64 v165, v[116:117] offset:2048
	v_or_b32_e32 v114, 32, v132
	v_mul_f32_e32 v116, v110, v136
	v_mul_f32_e32 v117, v111, v136
	v_mul_f32_e32 v112, v112, v136
	v_mul_f32_e32 v113, v113, v136
	v_mov_b32_e32 v115, v133
	v_lshl_add_u64 v[110:111], v[114:115], 1, s[2:3]
	v_cvt_pk_bf16_f32 v113, v112, v113
	v_cvt_pk_bf16_f32 v112, v116, v117
	ds_write_b64 v166, v[112:113]
	v_mul_f32_e32 v110, v106, v137
	v_mul_f32_e32 v111, v107, v137
	v_mul_f32_e32 v108, v108, v137
	v_mul_f32_e32 v109, v109, v137
	v_add_u32_e32 v106, 0x8020, v132
	v_mov_b32_e32 v107, v133
	v_lshl_add_u64 v[106:107], v[106:107], 1, s[2:3]
	v_cvt_pk_bf16_f32 v109, v108, v109
	v_cvt_pk_bf16_f32 v108, v110, v111
	ds_write_b64 v166, v[108:109] offset:2048
	v_or_b32_e32 v106, 48, v132
	v_mul_f32_e32 v108, v102, v136
	v_mul_f32_e32 v109, v103, v136
	v_mul_f32_e32 v104, v104, v136
	v_mul_f32_e32 v105, v105, v136
	v_mov_b32_e32 v107, v133
	v_lshl_add_u64 v[102:103], v[106:107], 1, s[2:3]
	v_cvt_pk_bf16_f32 v105, v104, v105
	v_cvt_pk_bf16_f32 v104, v108, v109
	ds_write_b64 v167, v[104:105]
	v_mul_f32_e32 v102, v98, v137
	v_mul_f32_e32 v103, v99, v137
	v_mul_f32_e32 v100, v100, v137
	v_mul_f32_e32 v101, v101, v137
	v_add_u32_e32 v98, 0x8030, v132
	v_mov_b32_e32 v99, v133
	v_lshl_add_u64 v[98:99], v[98:99], 1, s[2:3]
	v_cvt_pk_bf16_f32 v101, v100, v101
	v_cvt_pk_bf16_f32 v100, v102, v103
	ds_write_b64 v167, v[100:101] offset:2048
	v_add_u32_e32 v98, 0x40000, v132
	s_waitcnt lgkmcnt(0)
; DEVI float gelu_exact(float x) { return 0.5f * x * (1.f + erff(x * 0.70710678118654752f)); }
; template <int EPI, int NRM>
; DEVI void epilogue(acc_t& acc, int pn, int trow, const EpiArgs& e, const float* rl, bf16* shmx) {
;     ...
;     if (dst != nullptr) {
; #pragma unroll
;       for (int ai = 0; ai < 2; ++ai)
; #pragma unroll
;         for (int bj = 0; bj < 2; ++bj)
; #pragma unroll
;           for (int m = 0; m < 4; ++m)
; #pragma unroll
;             for (int n = 0; n < 2; ++n) {
;               float r[4];
; #pragma unroll
;               for (int j = 0; j < 4; ++j) { r[j] = acc[ai][bj][m][n][j] * rs[bj][n]; if (act) r[j] = gelu_exact(r[j]); }
;               uint2 o; o.x = pack2(r[0], r[1]); o.y = pack2(r[2], r[3]);
;               const unsigned off = (unsigned)((tk0 + bj * 128 + n * 16) * ldo + fbase + ai * 128 + m * 16 + fl0);
;               *reinterpret_cast<uint2*>(dst + off) = o;
;             }
	v_mul_f32_e32 v100, v94, v134
	v_mul_f32_e32 v101, v95, v134
	v_mul_f32_e32 v96, v96, v134
	v_mul_f32_e32 v97, v97, v134
	v_mov_b32_e32 v99, v133
	v_lshl_add_u64 v[94:95], v[98:99], 1, s[2:3]
	v_cvt_pk_bf16_f32 v97, v96, v97
	v_cvt_pk_bf16_f32 v96, v100, v101
	ds_write_b64 v164, v[96:97] offset:4096
	v_mul_f32_e32 v94, v90, v135
	v_mul_f32_e32 v95, v91, v135
	v_mul_f32_e32 v92, v92, v135
	v_mul_f32_e32 v93, v93, v135
	v_add_u32_e32 v90, 0x48000, v132
	v_mov_b32_e32 v91, v133
	v_lshl_add_u64 v[90:91], v[90:91], 1, s[2:3]
	v_cvt_pk_bf16_f32 v93, v92, v93
	v_cvt_pk_bf16_f32 v92, v94, v95
	ds_write_b64 v164, v[92:93] offset:6144
	v_add_u32_e32 v90, 0x40010, v132
	v_mul_f32_e32 v92, v86, v134
	v_mul_f32_e32 v93, v87, v134
	v_mul_f32_e32 v88, v88, v134
	v_mul_f32_e32 v89, v89, v134
	v_mov_b32_e32 v91, v133
	v_lshl_add_u64 v[86:87], v[90:91], 1, s[2:3]
	v_cvt_pk_bf16_f32 v89, v88, v89
	v_cvt_pk_bf16_f32 v88, v92, v93
	ds_write_b64 v165, v[88:89] offset:4096
	v_mul_f32_e32 v86, v82, v135
	v_mul_f32_e32 v87, v83, v135
	v_mul_f32_e32 v84, v84, v135
	v_mul_f32_e32 v85, v85, v135
	v_add_u32_e32 v82, 0x48010, v132
	v_mov_b32_e32 v83, v133
	v_lshl_add_u64 v[82:83], v[82:83], 1, s[2:3]
	v_cvt_pk_bf16_f32 v85, v84, v85
	v_cvt_pk_bf16_f32 v84, v86, v87
	ds_write_b64 v165, v[84:85] offset:6144
	v_add_u32_e32 v82, 0x40020, v132
	v_mul_f32_e32 v84, v78, v134
	v_mul_f32_e32 v85, v79, v134
	v_mul_f32_e32 v80, v80, v134
	v_mul_f32_e32 v81, v81, v134
	v_mov_b32_e32 v83, v133
	v_lshl_add_u64 v[78:79], v[82:83], 1, s[2:3]
	v_cvt_pk_bf16_f32 v81, v80, v81
	v_cvt_pk_bf16_f32 v80, v84, v85
	ds_write_b64 v166, v[80:81] offset:4096
	v_mul_f32_e32 v78, v74, v135
	v_mul_f32_e32 v79, v75, v135
	v_mul_f32_e32 v76, v76, v135
	v_mul_f32_e32 v77, v77, v135
	v_add_u32_e32 v74, 0x48020, v132
	v_mov_b32_e32 v75, v133
	v_lshl_add_u64 v[74:75], v[74:75], 1, s[2:3]
	v_cvt_pk_bf16_f32 v77, v76, v77
	v_cvt_pk_bf16_f32 v76, v78, v79
	ds_write_b64 v166, v[76:77] offset:6144
	v_add_u32_e32 v74, 0x40030, v132
	v_mul_f32_e32 v76, v70, v134
	v_mul_f32_e32 v77, v71, v134
	v_mul_f32_e32 v72, v72, v134
	v_mul_f32_e32 v73, v73, v134
	v_mov_b32_e32 v75, v133
	v_lshl_add_u64 v[70:71], v[74:75], 1, s[2:3]
	v_cvt_pk_bf16_f32 v73, v72, v73
	v_cvt_pk_bf16_f32 v72, v76, v77
	ds_write_b64 v167, v[72:73] offset:4096
	v_mul_f32_e32 v70, v62, v135
	v_mul_f32_e32 v71, v63, v135
	v_mul_f32_e32 v64, v64, v135
	v_mul_f32_e32 v65, v65, v135
	v_add_u32_e32 v62, 0x48030, v132
	v_mov_b32_e32 v63, v133
	v_lshl_add_u64 v[62:63], v[62:63], 1, s[2:3]
	v_cvt_pk_bf16_f32 v65, v64, v65
	v_cvt_pk_bf16_f32 v64, v70, v71
	ds_write_b64 v167, v[64:65] offset:6144
	s_waitcnt lgkmcnt(0)
	ds_read_b128 v[172:175], v168
	ds_read_b128 v[176:179], v168 offset:1024
	ds_read_b128 v[180:183], v168 offset:2048
	ds_read_b128 v[184:187], v168 offset:3072
	ds_read_b128 v[188:191], v168 offset:4096
	ds_read_b128 v[192:195], v168 offset:5120
	ds_read_b128 v[196:199], v168 offset:6144
	ds_read_b128 v[200:203], v168 offset:7168
	v_add_u32_e32 v204, 0x0, v169
	v_add_u32_e32 v205, 0x8000, v169
	v_add_u32_e32 v206, 0x10000, v169
	v_add_u32_e32 v207, 0x18000, v169
	v_add_u32_e32 v208, 0x80000, v169
	v_add_u32_e32 v209, 0x88000, v169
	v_add_u32_e32 v210, 0x90000, v169
	v_add_u32_e32 v211, 0x98000, v169
	s_waitcnt lgkmcnt(7)
	global_store_dwordx4 v204, v[172:175], s[2:3]
	s_waitcnt lgkmcnt(6)
	global_store_dwordx4 v205, v[176:179], s[2:3]
	s_waitcnt lgkmcnt(5)
	global_store_dwordx4 v206, v[180:183], s[2:3]
	s_waitcnt lgkmcnt(4)
	global_store_dwordx4 v207, v[184:187], s[2:3]
	s_waitcnt lgkmcnt(3)
	global_store_dwordx4 v208, v[188:191], s[2:3]
	s_waitcnt lgkmcnt(2)
	global_store_dwordx4 v209, v[192:195], s[2:3]
	s_waitcnt lgkmcnt(1)
	global_store_dwordx4 v210, v[196:199], s[2:3]
	s_waitcnt lgkmcnt(0)
; DEVI float gelu_exact(float x) { return 0.5f * x * (1.f + erff(x * 0.70710678118654752f)); }
; template <int EPI, int NRM>
; DEVI void epilogue(acc_t& acc, int pn, int trow, const EpiArgs& e, const float* rl, bf16* shmx) {
;     ...
;     if (dst != nullptr) {
; #pragma unroll
;       for (int ai = 0; ai < 2; ++ai)
; #pragma unroll
;         for (int bj = 0; bj < 2; ++bj)
; #pragma unroll
;           for (int m = 0; m < 4; ++m)
; #pragma unroll
;             for (int n = 0; n < 2; ++n) {
;               float r[4];
; #pragma unroll
;               for (int j = 0; j < 4; ++j) { r[j] = acc[ai][bj][m][n][j] * rs[bj][n]; if (act) r[j] = gelu_exact(r[j]); }
;               uint2 o; o.x = pack2(r[0], r[1]); o.y = pack2(r[2], r[3]);
;               const unsigned off = (unsigned)((tk0 + bj * 128 + n * 16) * ldo + fbase + ai * 128 + m * 16 + fl0);
;               *reinterpret_cast<uint2*>(dst + off) = o;
;             }
	global_store_dwordx4 v211, v[200:203], s[2:3]
	v_add_u32_e32 v62, 0x80, v132
	v_mul_f32_e32 v64, v66, v136
	v_mul_f32_e32 v66, v67, v136
	v_mul_f32_e32 v65, v68, v136
	v_mul_f32_e32 v67, v69, v136
	v_mov_b32_e32 v63, v133
	v_lshl_add_u64 v[62:63], v[62:63], 1, s[2:3]
	v_cvt_pk_bf16_f32 v65, v65, v67
	v_cvt_pk_bf16_f32 v64, v64, v66
	ds_write_b64 v164, v[64:65]
	v_mul_f32_e32 v62, v58, v137
	v_mul_f32_e32 v63, v59, v137
	v_mul_f32_e32 v60, v60, v137
	v_mul_f32_e32 v61, v61, v137
	v_add_u32_e32 v58, 0x8080, v132
	v_mov_b32_e32 v59, v133
	v_lshl_add_u64 v[58:59], v[58:59], 1, s[2:3]
	v_cvt_pk_bf16_f32 v61, v60, v61
	v_cvt_pk_bf16_f32 v60, v62, v63
	ds_write_b64 v164, v[60:61] offset:2048
	v_add_u32_e32 v58, 0x90, v132
	v_mul_f32_e32 v60, v54, v136
	v_mul_f32_e32 v61, v55, v136
	v_mul_f32_e32 v56, v56, v136
	v_mul_f32_e32 v57, v57, v136
	v_mov_b32_e32 v59, v133
	v_lshl_add_u64 v[54:55], v[58:59], 1, s[2:3]
	v_cvt_pk_bf16_f32 v57, v56, v57
	v_cvt_pk_bf16_f32 v56, v60, v61
	ds_write_b64 v165, v[56:57]
	v_mul_f32_e32 v54, v50, v137
	v_mul_f32_e32 v55, v51, v137
	v_mul_f32_e32 v52, v52, v137
	v_mul_f32_e32 v53, v53, v137
	v_add_u32_e32 v50, 0x8090, v132
	v_mov_b32_e32 v51, v133
	v_lshl_add_u64 v[50:51], v[50:51], 1, s[2:3]
	v_cvt_pk_bf16_f32 v53, v52, v53
	v_cvt_pk_bf16_f32 v52, v54, v55
	ds_write_b64 v165, v[52:53] offset:2048
	v_add_u32_e32 v50, 0xa0, v132
	v_mul_f32_e32 v52, v46, v136
	v_mul_f32_e32 v53, v47, v136
	v_mul_f32_e32 v48, v48, v136
	v_mul_f32_e32 v49, v49, v136
	v_mov_b32_e32 v51, v133
	v_lshl_add_u64 v[46:47], v[50:51], 1, s[2:3]
	v_cvt_pk_bf16_f32 v49, v48, v49
	v_cvt_pk_bf16_f32 v48, v52, v53
	ds_write_b64 v166, v[48:49]
	v_mul_f32_e32 v46, v42, v137
	v_mul_f32_e32 v47, v43, v137
	v_mul_f32_e32 v44, v44, v137
	v_mul_f32_e32 v45, v45, v137
	v_add_u32_e32 v42, 0x80a0, v132
	v_mov_b32_e32 v43, v133
	v_lshl_add_u64 v[42:43], v[42:43], 1, s[2:3]
	v_cvt_pk_bf16_f32 v45, v44, v45
	v_cvt_pk_bf16_f32 v44, v46, v47
	ds_write_b64 v166, v[44:45] offset:2048
	v_add_u32_e32 v42, 0xb0, v132
	v_mul_f32_e32 v44, v38, v136
	v_mul_f32_e32 v45, v39, v136
	v_mul_f32_e32 v40, v40, v136
	v_mul_f32_e32 v41, v41, v136
	v_mov_b32_e32 v43, v133
	v_lshl_add_u64 v[38:39], v[42:43], 1, s[2:3]
	v_cvt_pk_bf16_f32 v41, v40, v41
	v_cvt_pk_bf16_f32 v40, v44, v45
	ds_write_b64 v167, v[40:41]
	v_mul_f32_e32 v38, v34, v137
	v_mul_f32_e32 v39, v35, v137
	v_mul_f32_e32 v36, v36, v137
	v_mul_f32_e32 v37, v37, v137
	v_add_u32_e32 v34, 0x80b0, v132
	v_mov_b32_e32 v35, v133
	v_lshl_add_u64 v[34:35], v[34:35], 1, s[2:3]
	v_cvt_pk_bf16_f32 v37, v36, v37
	v_cvt_pk_bf16_f32 v36, v38, v39
	ds_write_b64 v167, v[36:37] offset:2048
	v_add_u32_e32 v34, 0x40080, v132
	v_mul_f32_e32 v36, v30, v134
	v_mul_f32_e32 v37, v31, v134
	v_mul_f32_e32 v32, v32, v134
	v_mul_f32_e32 v33, v33, v134
	v_mov_b32_e32 v35, v133
	v_lshl_add_u64 v[30:31], v[34:35], 1, s[2:3]
	v_cvt_pk_bf16_f32 v33, v32, v33
	v_cvt_pk_bf16_f32 v32, v36, v37
	ds_write_b64 v164, v[32:33] offset:4096
	v_mul_f32_e32 v30, v26, v135
	v_mul_f32_e32 v31, v27, v135
	v_mul_f32_e32 v28, v28, v135
	v_mul_f32_e32 v29, v29, v135
	v_add_u32_e32 v26, 0x48080, v132
	v_mov_b32_e32 v27, v133
	v_lshl_add_u64 v[26:27], v[26:27], 1, s[2:3]
	v_cvt_pk_bf16_f32 v29, v28, v29
	v_cvt_pk_bf16_f32 v28, v30, v31
	ds_write_b64 v164, v[28:29] offset:6144
	v_add_u32_e32 v26, 0x40090, v132
	v_mul_f32_e32 v28, v22, v134
	v_mul_f32_e32 v29, v23, v134
	v_mul_f32_e32 v24, v24, v134
	v_mul_f32_e32 v25, v25, v134
	v_mov_b32_e32 v27, v133
	v_lshl_add_u64 v[22:23], v[26:27], 1, s[2:3]
	v_cvt_pk_bf16_f32 v25, v24, v25
	v_cvt_pk_bf16_f32 v24, v28, v29
	ds_write_b64 v165, v[24:25] offset:4096
	v_mul_f32_e32 v22, v18, v135
	v_mul_f32_e32 v23, v19, v135
	v_mul_f32_e32 v20, v20, v135
	v_mul_f32_e32 v21, v21, v135
	v_add_u32_e32 v18, 0x48090, v132
	v_mov_b32_e32 v19, v133
	v_lshl_add_u64 v[18:19], v[18:19], 1, s[2:3]
	v_cvt_pk_bf16_f32 v21, v20, v21
	v_cvt_pk_bf16_f32 v20, v22, v23
	ds_write_b64 v165, v[20:21] offset:6144
	v_add_u32_e32 v18, 0x400a0, v132
	v_mul_f32_e32 v20, v14, v134
	v_mul_f32_e32 v21, v15, v134
	v_mul_f32_e32 v16, v16, v134
	v_mul_f32_e32 v17, v17, v134
	v_mov_b32_e32 v19, v133
	v_lshl_add_u64 v[14:15], v[18:19], 1, s[2:3]
	v_cvt_pk_bf16_f32 v17, v16, v17
	v_cvt_pk_bf16_f32 v16, v20, v21
	ds_write_b64 v166, v[16:17] offset:4096
	v_mul_f32_e32 v14, v10, v135
	v_mul_f32_e32 v15, v11, v135
	v_mul_f32_e32 v12, v12, v135
	v_mul_f32_e32 v13, v13, v135
	v_add_u32_e32 v10, 0x480a0, v132
	v_mov_b32_e32 v11, v133
	v_lshl_add_u64 v[10:11], v[10:11], 1, s[2:3]
	v_cvt_pk_bf16_f32 v13, v12, v13
	v_cvt_pk_bf16_f32 v12, v14, v15
	ds_write_b64 v166, v[12:13] offset:6144
	v_add_u32_e32 v10, 0x400b0, v132
	v_mul_f32_e32 v12, v6, v134
	v_mul_f32_e32 v13, v7, v134
	v_mul_f32_e32 v8, v8, v134
	v_mul_f32_e32 v9, v9, v134
	v_mov_b32_e32 v11, v133
	v_lshl_add_u64 v[6:7], v[10:11], 1, s[2:3]
	v_cvt_pk_bf16_f32 v9, v8, v9
	v_cvt_pk_bf16_f32 v8, v12, v13
	ds_write_b64 v167, v[8:9] offset:4096
	v_mul_f32_e32 v6, v2, v135
	v_mul_f32_e32 v7, v3, v135
	v_mul_f32_e32 v4, v4, v135
	v_mul_f32_e32 v5, v5, v135
	v_add_u32_e32 v132, 0x480b0, v132
	v_lshl_add_u64 v[2:3], v[132:133], 1, s[2:3]
	v_cvt_pk_bf16_f32 v5, v4, v5
	v_cvt_pk_bf16_f32 v4, v6, v7
	s_add_i32 s17, s17, 1
	s_andn2_b64 vcc, exec, s[4:5]
	s_mov_b32 s14, s8
	s_mov_b32 s12, s10
	ds_write_b64 v167, v[4:5] offset:6144
	s_waitcnt lgkmcnt(0)
	ds_read_b128 v[172:175], v168
	ds_read_b128 v[176:179], v168 offset:1024
	ds_read_b128 v[180:183], v168 offset:2048
	ds_read_b128 v[184:187], v168 offset:3072
	ds_read_b128 v[188:191], v168 offset:4096
	ds_read_b128 v[192:195], v168 offset:5120
	ds_read_b128 v[196:199], v168 offset:6144
	ds_read_b128 v[200:203], v168 offset:7168
	v_add_u32_e32 v204, 0x100, v169
	v_add_u32_e32 v205, 0x8100, v169
	v_add_u32_e32 v206, 0x10100, v169
	v_add_u32_e32 v207, 0x18100, v169
	v_add_u32_e32 v208, 0x80100, v169
	v_add_u32_e32 v209, 0x88100, v169
	v_add_u32_e32 v210, 0x90100, v169
	v_add_u32_e32 v211, 0x98100, v169
	s_waitcnt lgkmcnt(7)
	global_store_dwordx4 v204, v[172:175], s[2:3]
	s_waitcnt lgkmcnt(6)
	global_store_dwordx4 v205, v[176:179], s[2:3]
	s_waitcnt lgkmcnt(5)
	global_store_dwordx4 v206, v[180:183], s[2:3]
	s_waitcnt lgkmcnt(4)
	global_store_dwordx4 v207, v[184:187], s[2:3]
	s_waitcnt lgkmcnt(3)
	global_store_dwordx4 v208, v[188:191], s[2:3]
	s_waitcnt lgkmcnt(2)
	global_store_dwordx4 v209, v[192:195], s[2:3]
	s_waitcnt lgkmcnt(1)
	global_store_dwordx4 v210, v[196:199], s[2:3]
	s_waitcnt lgkmcnt(0)
	global_store_dwordx4 v211, v[200:203], s[2:3]
	s_cbranch_vccz .LBB0_1912
